# tail units: direct branch into/out of the down-GEMM phase code for idle WGs (no kernel re-entry), deferred producer signal (wbl2 at unit 2, flag post at unit 3)
# speedup vs baseline: 1.0805x; 1.0200x over previous
.Lp_reentry:
	s_load_dwordx2 s[94:95], s[0:1], 0xd0
	s_load_dwordx4 s[4:7], s[0:1], 0xc0
	s_load_dword s16, s[0:1], 0xe8
	s_load_dwordx4 s[12:15], s[0:1], 0xd8
	s_load_dwordx2 s[34:35], s[0:1], 0xf0
	v_and_b32_e32 v175, 0x3ff, v0
	v_cmp_gt_u32_e32 vcc, 64, v175
	s_waitcnt lgkmcnt(0)
	v_writelane_b32 v254, s4, 0
	s_nop 1
	v_writelane_b32 v254, s5, 1
	v_writelane_b32 v254, s6, 2
	v_writelane_b32 v254, s7, 3
	s_add_u32 s6, s0, 0xf0
	s_addc_u32 s7, s1, 0
	s_and_saveexec_b64 s[4:5], vcc
	v_lshl_add_u32 v1, v175, 2, 0
	v_add_u32_e32 v1, 0x20000, v1
	v_mov_b32_e32 v2, 0
	ds_write_b32 v1, v2
	s_or_b64 exec, exec, s[4:5]
	s_load_dword s75, s[0:1], 0xf8
	s_waitcnt lgkmcnt(0)
	s_barrier
	s_add_u32 s76, s94, 0x1000
	s_getreg_b32 s3, hwreg(HW_REG_XCC_ID, 0, 4)
	s_addc_u32 s77, s95, 0
	s_and_b32 s33, s3, 15
	v_cmp_eq_u32_e64 s[8:9], 0, v175
	s_mov_b64 s[4:5], exec
	s_nop 0
	v_writelane_b32 v254, s8, 4
	s_nop 1
	v_writelane_b32 v254, s9, 5
	s_and_b64 s[8:9], s[4:5], s[8:9]
	s_mov_b64 exec, s[8:9]
	s_cbranch_execz .LBB0_5
	s_mov_b64 s[8:9], exec
	v_mbcnt_lo_u32_b32 v1, s8, 0
	v_mbcnt_hi_u32_b32 v1, s9, v1
	v_cmp_eq_u32_e32 vcc, 0, v1
	s_and_b64 s[10:11], exec, vcc
	s_mov_b64 exec, s[10:11]
	s_cbranch_execz .LBB0_5
	s_lshl_b32 s3, s33, 8
	s_bcnt1_i32_b64 s8, s[8:9]
	v_mov_b32_e32 v1, s3
	v_mov_b32_e32 v2, s8
	global_atomic_add v1, v2, s[76:77] offset:1024

.LBB0_310:
	s_cmp_lt_i32 s84, 4
	s_cselect_b64 s[4:5], -1, 0
	s_add_u32 s18, s94, 0x6a00000
	s_addc_u32 s19, s95, 0
	s_and_b64 s[4:5], s[4:5], s[0:1]
	s_andn2_b64 vcc, exec, s[4:5]
	s_cbranch_vccnz .LBB0_335
	s_mov_b32 s99, 0
	s_cmp_eq_u32 s98, 2
	s_cbranch_scc1 .LBB0_335
	s_cmpk_gt_i32 s2, 0x5ab
	v_readfirstlane_b32 s8, v175
	s_cbranch_scc1 .LBB0_335
	s_ashr_i32 s3, s2, 31
	s_lshr_b32 s0, s3, 29
	s_add_i32 s7, s2, s0
	s_and_b32 s0, s7, -8
	s_sub_i32 s9, s2, s0
	s_cmp_gt_i32 s9, 3
	s_cbranch_scc0 .LBB0_314
	s_mul_i32 s0, s9, 0xb5
	s_add_i32 s6, s0, 4
	s_cbranch_execz .LBB0_315
	s_branch .LBB0_316

.LBB0_331:
	s_cmp_eq_u32 s99, 0
	s_cbranch_scc1 .Lsd3_x
	s_cmp_lt_u32 s15, 3
	s_cbranch_scc1 .Lsd3_x
	s_cmp_gt_u32 s15, 4
	s_cbranch_scc1 .Lsd3_x
	v_cmp_gt_u32_e32 vcc, 64, v175
	s_cbranch_vccz .Lsd3_x
	s_cmp_eq_u32 s15, 3
	s_cbranch_scc0 .Lsd3_b
	buffer_wbl2 sc1
	s_branch .Lsd3_x
.Lsd3_b:
	s_waitcnt vmcnt(0)
	s_mov_b64 exec, 1
	v_mov_b32_e32 v157, 0x4a00
	v_mov_b32_e32 v160, s99
	global_atomic_add v157, v160, s[94:95]
	s_nop 1
	s_mov_b64 exec, -1
.Lsd3_x:
	v_mul_f32_e32 v157, 0xbfb8aa3b, v124
	v_exp_f32_e32 v157, v157
	v_mul_f32_e32 v160, 0xbfb8aa3b, v125
	v_exp_f32_e32 v160, v160
	v_lshl_or_b32 v148, s37, 7, v152
	v_add_f32_e32 v157, 1.0, v157
	v_rcp_f32_e32 v157, v157
	v_add_f32_e32 v160, 1.0, v160
	v_rcp_f32_e32 v160, v160
	v_lshl_add_u32 v156, s58, 8, v150
	v_mul_f32_e32 v124, v124, v157
	v_mul_f32_e32 v116, v116, v124
	v_mul_f32_e32 v124, v125, v160
	v_mul_f32_e32 v125, 0xbfb8aa3b, v126
	v_exp_f32_e32 v125, v125
	v_mul_f32_e32 v157, 0xbfb8aa3b, v127
	v_exp_f32_e32 v157, v157
	v_mul_f32_e32 v117, v117, v124
	v_add_f32_e32 v124, 1.0, v125
	v_rcp_f32_e32 v124, v124
	v_add_f32_e32 v125, 1.0, v157
	v_rcp_f32_e32 v125, v125
	v_cvt_pk_bf16_f32 v116, v116, v117
	v_mul_f32_e32 v117, v126, v124
	v_mul_f32_e32 v124, 0xbfb8aa3b, v120
	v_exp_f32_e32 v124, v124
	v_mul_f32_e32 v117, v118, v117
	v_mul_f32_e32 v118, v127, v125
	v_mul_f32_e32 v125, 0xbfb8aa3b, v121
	v_exp_f32_e32 v125, v125
	v_mul_f32_e32 v118, v119, v118
	v_add_f32_e32 v119, 1.0, v124
	v_rcp_f32_e32 v119, v119
	v_add_f32_e32 v124, 1.0, v125
	v_rcp_f32_e32 v124, v124
	v_cvt_pk_bf16_f32 v117, v117, v118
	v_mul_f32_e32 v118, v120, v119
	v_mul_f32_e32 v119, 0xbfb8aa3b, v122
	v_exp_f32_e32 v119, v119
	v_mul_f32_e32 v120, 0xbfb8aa3b, v123
	v_exp_f32_e32 v120, v120
	v_mul_f32_e32 v112, v112, v118
	v_mul_f32_e32 v118, v121, v124
	v_mul_f32_e32 v113, v113, v118
	v_add_f32_e32 v118, 1.0, v119
	v_rcp_f32_e32 v119, v118
	v_add_f32_e32 v118, 1.0, v120
	v_rcp_f32_e32 v120, v118
	v_cvt_pk_bf16_f32 v118, v112, v113
	v_mul_f32_e32 v112, v122, v119
	v_mul_f32_e32 v112, v114, v112
	v_mul_f32_e32 v113, v123, v120
	v_mul_f32_e32 v113, v115, v113
	v_cvt_pk_bf16_f32 v119, v112, v113
	v_mul_f32_e32 v113, 0xbfb8aa3b, v108
	v_exp_f32_e32 v114, v113
	v_mul_f32_e32 v113, 0xbfb8aa3b, v109
	v_exp_f32_e32 v115, v113
	v_ashrrev_i32_e32 v149, 31, v148
	v_add_f32_e32 v114, 1.0, v114
	v_rcp_f32_e32 v114, v114
	v_add_f32_e32 v115, 1.0, v115
	v_rcp_f32_e32 v115, v115
	v_mov_b64_e32 v[146:147], s[18:19]
	v_mul_f32_e32 v108, v108, v114
	v_mul_f32_e32 v100, v100, v108
	v_mul_f32_e32 v108, v109, v115
	v_mul_f32_e32 v109, 0xbfb8aa3b, v110
	v_exp_f32_e32 v109, v109
	v_mul_f32_e32 v114, 0xbfb8aa3b, v111
	v_exp_f32_e32 v114, v114
	v_mul_f32_e32 v101, v101, v108
	v_add_f32_e32 v108, 1.0, v109
	v_rcp_f32_e32 v108, v108
	v_mad_i64_i32 v[158:159], s[6:7], v156, s36, v[146:147]
	v_lshlrev_b64 v[148:149], 1, v[148:149]
	v_lshl_add_u64 v[158:159], v[158:159], 0, v[148:149]
	v_add_f32_e32 v109, 1.0, v114
	global_store_dwordx4 v[158:159], v[116:119], off
	v_rcp_f32_e32 v109, v109
	v_cvt_pk_bf16_f32 v100, v100, v101
	v_mul_f32_e32 v101, v110, v108
	v_mul_f32_e32 v108, 0xbfb8aa3b, v104
	v_exp_f32_e32 v108, v108
	v_mul_f32_e32 v101, v102, v101
	v_mul_f32_e32 v102, v111, v109
	v_mul_f32_e32 v109, 0xbfb8aa3b, v105
	v_exp_f32_e32 v109, v109
	v_mul_f32_e32 v102, v103, v102
	v_add_f32_e32 v103, 1.0, v108
	v_rcp_f32_e32 v103, v103
	v_add_f32_e32 v108, 1.0, v109
	v_rcp_f32_e32 v108, v108
	v_cvt_pk_bf16_f32 v101, v101, v102
	v_mul_f32_e32 v102, v104, v103
	v_mul_f32_e32 v103, 0xbfb8aa3b, v106
	v_exp_f32_e32 v103, v103
	v_mul_f32_e32 v104, 0xbfb8aa3b, v107
	v_exp_f32_e32 v104, v104
	v_mul_f32_e32 v96, v96, v102
	v_mul_f32_e32 v102, v105, v108
	v_mul_f32_e32 v97, v97, v102
	v_add_f32_e32 v102, 1.0, v103
	v_rcp_f32_e32 v103, v102
	v_add_f32_e32 v102, 1.0, v104
	v_rcp_f32_e32 v104, v102
	v_cvt_pk_bf16_f32 v102, v96, v97
	v_mul_f32_e32 v96, v106, v103
	v_mul_f32_e32 v96, v98, v96
	v_mul_f32_e32 v97, v107, v104
	v_mul_f32_e32 v97, v99, v97
	v_cvt_pk_bf16_f32 v103, v96, v97
	v_mul_f32_e32 v97, 0xbfb8aa3b, v92
	v_exp_f32_e32 v98, v97
	v_mul_f32_e32 v97, 0xbfb8aa3b, v93
	v_exp_f32_e32 v99, v97
	v_or_b32_e32 v112, 16, v156
	v_add_f32_e32 v98, 1.0, v98
	v_rcp_f32_e32 v98, v98
	v_add_f32_e32 v99, 1.0, v99
	v_rcp_f32_e32 v99, v99
	v_mad_i64_i32 v[112:113], s[6:7], v112, s36, v[146:147]
	v_mul_f32_e32 v92, v92, v98
	v_mul_f32_e32 v84, v84, v92
	v_mul_f32_e32 v92, v93, v99
	v_mul_f32_e32 v93, 0xbfb8aa3b, v94
	v_exp_f32_e32 v93, v93
	v_mul_f32_e32 v98, 0xbfb8aa3b, v95
	v_exp_f32_e32 v98, v98
	v_mul_f32_e32 v85, v85, v92
	v_add_f32_e32 v92, 1.0, v93
	v_rcp_f32_e32 v92, v92
	v_lshl_add_u64 v[112:113], v[112:113], 0, v[148:149]
	v_add_f32_e32 v93, 1.0, v98
	global_store_dwordx4 v[112:113], v[100:103], off
	v_rcp_f32_e32 v93, v93
	v_cvt_pk_bf16_f32 v84, v84, v85
	v_mul_f32_e32 v85, v94, v92
	v_mul_f32_e32 v92, 0xbfb8aa3b, v88
	v_exp_f32_e32 v92, v92
	v_mul_f32_e32 v85, v86, v85
	v_mul_f32_e32 v86, v95, v93
	v_mul_f32_e32 v93, 0xbfb8aa3b, v89
	v_exp_f32_e32 v93, v93
	v_mul_f32_e32 v86, v87, v86
	v_add_f32_e32 v87, 1.0, v92
	v_rcp_f32_e32 v87, v87
	v_add_f32_e32 v92, 1.0, v93
	v_rcp_f32_e32 v92, v92
	v_cvt_pk_bf16_f32 v85, v85, v86
	v_mul_f32_e32 v86, v88, v87
	v_mul_f32_e32 v87, 0xbfb8aa3b, v90
	v_exp_f32_e32 v87, v87
	v_mul_f32_e32 v88, 0xbfb8aa3b, v91
	v_exp_f32_e32 v88, v88
	v_mul_f32_e32 v80, v80, v86
	v_mul_f32_e32 v86, v89, v92
	v_mul_f32_e32 v81, v81, v86
	v_add_f32_e32 v86, 1.0, v87
	v_rcp_f32_e32 v87, v86
	v_add_f32_e32 v86, 1.0, v88
	v_rcp_f32_e32 v88, v86
	v_cvt_pk_bf16_f32 v86, v80, v81
	v_mul_f32_e32 v80, v90, v87
	v_mul_f32_e32 v80, v82, v80
	v_mul_f32_e32 v81, v91, v88
	v_mul_f32_e32 v81, v83, v81
	v_cvt_pk_bf16_f32 v87, v80, v81
	v_mul_f32_e32 v81, 0xbfb8aa3b, v76
	v_exp_f32_e32 v82, v81
	v_mul_f32_e32 v81, 0xbfb8aa3b, v77
	v_exp_f32_e32 v83, v81
	v_or_b32_e32 v96, 32, v156
	v_add_f32_e32 v82, 1.0, v82
	v_rcp_f32_e32 v82, v82
	v_add_f32_e32 v83, 1.0, v83
	v_rcp_f32_e32 v83, v83
	v_mad_i64_i32 v[96:97], s[6:7], v96, s36, v[146:147]
	v_mul_f32_e32 v76, v76, v82
	v_mul_f32_e32 v68, v68, v76
	v_mul_f32_e32 v76, v77, v83
	v_mul_f32_e32 v77, 0xbfb8aa3b, v78
	v_exp_f32_e32 v77, v77
	v_mul_f32_e32 v82, 0xbfb8aa3b, v79
	v_exp_f32_e32 v82, v82
	v_mul_f32_e32 v69, v69, v76
	v_add_f32_e32 v76, 1.0, v77
	v_rcp_f32_e32 v76, v76
	v_lshl_add_u64 v[96:97], v[96:97], 0, v[148:149]
	v_add_f32_e32 v77, 1.0, v82
	global_store_dwordx4 v[96:97], v[84:87], off
	v_rcp_f32_e32 v77, v77
	v_cvt_pk_bf16_f32 v68, v68, v69
	v_mul_f32_e32 v69, v78, v76
	v_mul_f32_e32 v76, 0xbfb8aa3b, v72
	v_exp_f32_e32 v76, v76
	v_mul_f32_e32 v69, v70, v69
	v_mul_f32_e32 v70, v79, v77
	v_mul_f32_e32 v77, 0xbfb8aa3b, v73
	v_exp_f32_e32 v77, v77
	v_mul_f32_e32 v70, v71, v70
	v_add_f32_e32 v71, 1.0, v76
	v_rcp_f32_e32 v71, v71
	v_add_f32_e32 v76, 1.0, v77
	v_rcp_f32_e32 v76, v76
	v_cvt_pk_bf16_f32 v69, v69, v70
	v_mul_f32_e32 v70, v72, v71
	v_mul_f32_e32 v71, 0xbfb8aa3b, v74
	v_exp_f32_e32 v71, v71
	v_mul_f32_e32 v72, 0xbfb8aa3b, v75
	v_exp_f32_e32 v72, v72
	v_mul_f32_e32 v64, v64, v70
	v_mul_f32_e32 v70, v73, v76
	v_mul_f32_e32 v65, v65, v70
	v_add_f32_e32 v70, 1.0, v71
	v_rcp_f32_e32 v71, v70
	v_add_f32_e32 v70, 1.0, v72
	v_rcp_f32_e32 v72, v70
	v_cvt_pk_bf16_f32 v70, v64, v65
	v_mul_f32_e32 v64, v74, v71
	v_mul_f32_e32 v64, v66, v64
	v_mul_f32_e32 v65, v75, v72
	v_mul_f32_e32 v65, v67, v65
	v_cvt_pk_bf16_f32 v71, v64, v65
	v_mul_f32_e32 v65, 0xbfb8aa3b, v60
	v_exp_f32_e32 v66, v65
	v_mul_f32_e32 v65, 0xbfb8aa3b, v61
	v_exp_f32_e32 v67, v65
	v_or_b32_e32 v80, 48, v156
	v_add_f32_e32 v66, 1.0, v66
	v_rcp_f32_e32 v66, v66
	v_add_f32_e32 v67, 1.0, v67
	v_rcp_f32_e32 v67, v67
	v_mad_i64_i32 v[80:81], s[6:7], v80, s36, v[146:147]
	v_mul_f32_e32 v60, v60, v66
	v_mul_f32_e32 v52, v52, v60
	v_mul_f32_e32 v60, v61, v67
	v_mul_f32_e32 v61, 0xbfb8aa3b, v62
	v_exp_f32_e32 v61, v61
	v_mul_f32_e32 v66, 0xbfb8aa3b, v63
	v_exp_f32_e32 v66, v66
	v_mul_f32_e32 v53, v53, v60
	v_add_f32_e32 v60, 1.0, v61
	v_rcp_f32_e32 v60, v60
	v_lshl_add_u64 v[80:81], v[80:81], 0, v[148:149]
	v_add_f32_e32 v61, 1.0, v66
	global_store_dwordx4 v[80:81], v[68:71], off
	v_rcp_f32_e32 v61, v61
	v_cvt_pk_bf16_f32 v52, v52, v53
	v_mul_f32_e32 v53, v62, v60
	v_mul_f32_e32 v60, 0xbfb8aa3b, v56
	v_exp_f32_e32 v60, v60
	v_mul_f32_e32 v53, v54, v53
	v_mul_f32_e32 v54, v63, v61
	v_mul_f32_e32 v61, 0xbfb8aa3b, v57
	v_exp_f32_e32 v61, v61
	v_mul_f32_e32 v54, v55, v54
	v_add_f32_e32 v55, 1.0, v60
	v_rcp_f32_e32 v55, v55
	v_add_f32_e32 v60, 1.0, v61
	v_rcp_f32_e32 v60, v60
	v_cvt_pk_bf16_f32 v53, v53, v54
	v_mul_f32_e32 v54, v56, v55
	v_mul_f32_e32 v55, 0xbfb8aa3b, v58
	v_exp_f32_e32 v55, v55
	v_mul_f32_e32 v56, 0xbfb8aa3b, v59
	v_exp_f32_e32 v56, v56
	v_mul_f32_e32 v48, v48, v54
	v_mul_f32_e32 v54, v57, v60
	v_mul_f32_e32 v49, v49, v54
	v_add_f32_e32 v54, 1.0, v55
	v_rcp_f32_e32 v55, v54
	v_add_f32_e32 v54, 1.0, v56
	v_rcp_f32_e32 v56, v54
	v_cvt_pk_bf16_f32 v54, v48, v49
	v_mul_f32_e32 v48, v58, v55
	v_mul_f32_e32 v48, v50, v48
	v_mul_f32_e32 v49, v59, v56
	v_mul_f32_e32 v49, v51, v49
	v_cvt_pk_bf16_f32 v55, v48, v49
	v_mul_f32_e32 v49, 0xbfb8aa3b, v44
	v_exp_f32_e32 v50, v49
	v_mul_f32_e32 v49, 0xbfb8aa3b, v45
	v_exp_f32_e32 v51, v49
	v_add_u32_e32 v64, 0x80, v156
	v_add_f32_e32 v50, 1.0, v50
	v_rcp_f32_e32 v50, v50
	v_add_f32_e32 v51, 1.0, v51
	v_rcp_f32_e32 v51, v51
	v_mad_i64_i32 v[64:65], s[6:7], v64, s36, v[146:147]
	v_mul_f32_e32 v44, v44, v50
	v_mul_f32_e32 v36, v36, v44
	v_mul_f32_e32 v44, v45, v51
	v_mul_f32_e32 v45, 0xbfb8aa3b, v46
	v_exp_f32_e32 v45, v45
	v_mul_f32_e32 v50, 0xbfb8aa3b, v47
	v_exp_f32_e32 v50, v50
	v_mul_f32_e32 v37, v37, v44
	v_add_f32_e32 v44, 1.0, v45
	v_rcp_f32_e32 v44, v44
	v_lshl_add_u64 v[64:65], v[64:65], 0, v[148:149]
	v_add_f32_e32 v45, 1.0, v50
	global_store_dwordx4 v[64:65], v[52:55], off
	v_rcp_f32_e32 v45, v45
	v_cvt_pk_bf16_f32 v36, v36, v37
	v_mul_f32_e32 v37, v46, v44
	v_mul_f32_e32 v44, 0xbfb8aa3b, v40
	v_exp_f32_e32 v44, v44
	v_mul_f32_e32 v37, v38, v37
	v_mul_f32_e32 v38, v47, v45
	v_mul_f32_e32 v45, 0xbfb8aa3b, v41
	v_exp_f32_e32 v45, v45
	v_mul_f32_e32 v38, v39, v38
	v_add_f32_e32 v39, 1.0, v44
	v_rcp_f32_e32 v39, v39
	v_add_f32_e32 v44, 1.0, v45
	v_rcp_f32_e32 v44, v44
	v_cvt_pk_bf16_f32 v37, v37, v38
	v_mul_f32_e32 v38, v40, v39
	v_mul_f32_e32 v39, 0xbfb8aa3b, v42
	v_exp_f32_e32 v39, v39
	v_mul_f32_e32 v40, 0xbfb8aa3b, v43
	v_exp_f32_e32 v40, v40
	v_mul_f32_e32 v32, v32, v38
	v_mul_f32_e32 v38, v41, v44
	v_mul_f32_e32 v33, v33, v38
	v_add_f32_e32 v38, 1.0, v39
	v_rcp_f32_e32 v39, v38
	v_add_f32_e32 v38, 1.0, v40
	v_rcp_f32_e32 v40, v38
	v_cvt_pk_bf16_f32 v38, v32, v33
	v_mul_f32_e32 v32, v42, v39
	v_mul_f32_e32 v32, v34, v32
	v_mul_f32_e32 v33, v43, v40
	v_mul_f32_e32 v33, v35, v33
	v_cvt_pk_bf16_f32 v39, v32, v33
	v_mul_f32_e32 v33, 0xbfb8aa3b, v28
	v_exp_f32_e32 v34, v33
	v_mul_f32_e32 v33, 0xbfb8aa3b, v29
	v_exp_f32_e32 v35, v33
	v_add_u32_e32 v48, 0x90, v156
	v_add_f32_e32 v34, 1.0, v34
	v_rcp_f32_e32 v34, v34
	v_add_f32_e32 v35, 1.0, v35
	v_rcp_f32_e32 v35, v35
	v_mad_i64_i32 v[48:49], s[6:7], v48, s36, v[146:147]
	v_mul_f32_e32 v28, v28, v34
	v_mul_f32_e32 v20, v20, v28
	v_mul_f32_e32 v28, v29, v35
	v_mul_f32_e32 v29, 0xbfb8aa3b, v30
	v_exp_f32_e32 v29, v29
	v_mul_f32_e32 v34, 0xbfb8aa3b, v31
	v_exp_f32_e32 v34, v34
	v_mul_f32_e32 v21, v21, v28
	v_add_f32_e32 v28, 1.0, v29
	v_rcp_f32_e32 v28, v28
	v_lshl_add_u64 v[48:49], v[48:49], 0, v[148:149]
	v_add_f32_e32 v29, 1.0, v34
	global_store_dwordx4 v[48:49], v[36:39], off
	v_rcp_f32_e32 v29, v29
	v_cvt_pk_bf16_f32 v20, v20, v21
	v_mul_f32_e32 v21, v30, v28
	v_mul_f32_e32 v28, 0xbfb8aa3b, v24
	v_exp_f32_e32 v28, v28
	v_mul_f32_e32 v21, v22, v21
	v_mul_f32_e32 v22, v31, v29
	v_mul_f32_e32 v29, 0xbfb8aa3b, v25
	v_exp_f32_e32 v29, v29
	v_mul_f32_e32 v22, v23, v22
	v_add_f32_e32 v23, 1.0, v28
	v_rcp_f32_e32 v23, v23
	v_add_f32_e32 v28, 1.0, v29
	v_rcp_f32_e32 v28, v28
	v_cvt_pk_bf16_f32 v21, v21, v22
	v_mul_f32_e32 v22, v24, v23
	v_mul_f32_e32 v23, 0xbfb8aa3b, v26
	v_exp_f32_e32 v23, v23
	v_mul_f32_e32 v24, 0xbfb8aa3b, v27
	v_exp_f32_e32 v24, v24
	v_mul_f32_e32 v16, v16, v22
	v_mul_f32_e32 v22, v25, v28
	v_mul_f32_e32 v17, v17, v22
	v_add_f32_e32 v22, 1.0, v23
	v_rcp_f32_e32 v23, v22
	v_add_f32_e32 v22, 1.0, v24
	v_rcp_f32_e32 v24, v22
	v_cvt_pk_bf16_f32 v22, v16, v17
	v_mul_f32_e32 v16, v26, v23
	v_mul_f32_e32 v16, v18, v16
	v_mul_f32_e32 v17, v27, v24
	v_mul_f32_e32 v17, v19, v17
	v_cvt_pk_bf16_f32 v23, v16, v17
	v_mul_f32_e32 v17, 0xbfb8aa3b, v12
	v_exp_f32_e32 v18, v17
	v_mul_f32_e32 v17, 0xbfb8aa3b, v13
	v_exp_f32_e32 v19, v17
	v_add_u32_e32 v32, 0xa0, v156
	v_add_f32_e32 v18, 1.0, v18
	v_rcp_f32_e32 v18, v18
	v_add_f32_e32 v19, 1.0, v19
	v_rcp_f32_e32 v19, v19
	v_mad_i64_i32 v[32:33], s[6:7], v32, s36, v[146:147]
	v_mul_f32_e32 v12, v12, v18
	v_mul_f32_e32 v4, v4, v12
	v_mul_f32_e32 v12, v13, v19
	v_mul_f32_e32 v13, 0xbfb8aa3b, v14
	v_exp_f32_e32 v13, v13
	v_mul_f32_e32 v18, 0xbfb8aa3b, v15
	v_exp_f32_e32 v18, v18
	v_mul_f32_e32 v5, v5, v12
	v_add_f32_e32 v12, 1.0, v13
	v_rcp_f32_e32 v12, v12
	v_lshl_add_u64 v[32:33], v[32:33], 0, v[148:149]
	v_add_f32_e32 v13, 1.0, v18
	global_store_dwordx4 v[32:33], v[20:23], off
	v_rcp_f32_e32 v13, v13
	v_cvt_pk_bf16_f32 v4, v4, v5
	v_mul_f32_e32 v5, v14, v12
	v_mul_f32_e32 v12, 0xbfb8aa3b, v8
	v_exp_f32_e32 v12, v12
	v_mul_f32_e32 v5, v6, v5
	v_mul_f32_e32 v6, v15, v13
	v_mul_f32_e32 v13, 0xbfb8aa3b, v9
	v_exp_f32_e32 v13, v13
	v_mul_f32_e32 v6, v7, v6
	v_add_f32_e32 v7, 1.0, v12
	v_rcp_f32_e32 v7, v7
	v_add_f32_e32 v12, 1.0, v13
	v_rcp_f32_e32 v12, v12
	v_cvt_pk_bf16_f32 v5, v5, v6
	v_mul_f32_e32 v6, v8, v7
	v_mul_f32_e32 v7, 0xbfb8aa3b, v10
	v_exp_f32_e32 v7, v7
	v_mul_f32_e32 v8, 0xbfb8aa3b, v11
	v_exp_f32_e32 v8, v8
	v_mul_f32_e32 v0, v0, v6
	v_mul_f32_e32 v6, v9, v12
	v_mul_f32_e32 v1, v1, v6
	v_add_f32_e32 v6, 1.0, v7
	v_rcp_f32_e32 v7, v6
	v_add_f32_e32 v6, 1.0, v8
	v_rcp_f32_e32 v8, v6
	v_add_u32_e32 v16, 0xb0, v156
	v_mad_i64_i32 v[16:17], s[6:7], v16, s36, v[146:147]
	v_lshl_add_u64 v[16:17], v[16:17], 0, v[148:149]
	v_cvt_pk_bf16_f32 v6, v0, v1
	v_mul_f32_e32 v0, v10, v7
	v_mul_f32_e32 v1, v11, v8
	s_andn2_b64 vcc, exec, s[0:1]
	s_mov_b64 s[0:1], -1
	v_mul_f32_e32 v0, v2, v0
	v_mul_f32_e32 v1, v3, v1
	v_cvt_pk_bf16_f32 v7, v0, v1
	global_store_dwordx4 v[16:17], v[4:7], off
	s_cmp_lt_i32 s58, 64
	s_cbranch_scc1 .Lsd3_e
	s_add_u32 s99, s99, 1

.LBB0_335:
	s_cmp_gt_i32 s85, 4
	s_cselect_b64 s[0:1], -1, 0
	s_and_b64 s[4:5], s[4:5], s[0:1]
	s_andn2_b64 vcc, exec, s[4:5]
	s_cbranch_vccnz .LBB0_387
	s_cmp_lg_u32 s98, 0
	s_cbranch_scc1 .Ltg3_no
	s_cmp_lt_u32 s2, 172
	s_cbranch_scc1 .Ltg3_no
	s_cmp_gt_u32 s2, 251
	s_cbranch_scc1 .Ltg3_no
	s_mov_b32 s98, 1
	s_add_u32 s26, s94, 0xe600000
	s_addc_u32 s27, s95, 0
	s_add_u32 s22, s94, 0xc500000
	s_addc_u32 s23, s95, 0
	s_branch .Ld4_body

.Ld4_body:
	s_cmpk_lg_i32 s34, 0x100
	s_cselect_b64 s[4:5], -1, 0
	s_cmpk_gt_i32 s2, 0x57
	s_cselect_b64 s[6:7], -1, 0
	s_mov_b64 s[30:31], -1
	v_readfirstlane_b32 s28, v175
	s_and_b64 vcc, exec, s[30:31]
	s_cbranch_vccz .LBB0_391
	s_cmpk_gt_i32 s2, 0xff
	s_mov_b64 s[8:9], 0
	s_cbranch_scc0 .LBB0_392
	s_add_u32 s4, s2, 0xffffff00
	s_addc_u32 s5, 0, -1
	s_waitcnt vmcnt(0)
	v_mov_b64_e32 v[0:1], 0x58
	v_cmp_lt_u64_e64 s[6:7], s[4:5], v[0:1]
	s_mov_b64 s[10:11], 0
	s_andn2_b64 vcc, exec, s[10:11]
	s_cbranch_vccnz .LBB0_398
	s_branch .LBB0_393

.LBB0_439:
	s_cmp_lg_u32 s98, 1
	s_cbranch_scc1 .Ld4_cont
	s_mov_b32 s98, 2
	s_cmp_gt_i32 s85, 4
	s_cselect_b64 s[0:1], -1, 0
	v_readlane_b32 s99, v255, 63
	v_mbcnt_lo_u32_b32 v175, -1, 0
	v_mbcnt_hi_u32_b32 v175, -1, v175
	s_nop 1
	v_add_u32_e32 v175, s99, v175
	s_branch .Ltg3_no

.LBB0_1205:
	s_cmp_lt_i32 s84, 12
	s_cselect_b64 s[4:5], -1, 0
	s_and_b64 s[4:5], s[4:5], s[0:1]
	s_andn2_b64 vcc, exec, s[4:5]
	s_cbranch_vccnz .LBB0_1230
	s_mov_b32 s99, 0
	s_cmp_eq_u32 s98, 4
	s_cbranch_scc1 .LBB0_1230
	s_cmpk_gt_i32 s2, 0x5ab
	v_readfirstlane_b32 s12, v175
	s_cbranch_scc1 .LBB0_1230
	s_ashr_i32 s3, s2, 31
	s_lshr_b32 s0, s3, 29
	s_add_i32 s7, s2, s0
	s_and_b32 s0, s7, -8
	s_sub_i32 s8, s2, s0
	s_cmp_gt_i32 s8, 3
	s_cbranch_scc0 .LBB0_1209
	s_mul_i32 s0, s8, 0xb5
	s_add_i32 s6, s0, 4
	s_cbranch_execz .LBB0_1210
	s_branch .LBB0_1211

.LBB0_1226:
	s_cmp_eq_u32 s99, 0
	s_cbranch_scc1 .Lsd11_x
	s_cmp_lt_u32 s46, 3
	s_cbranch_scc1 .Lsd11_x
	s_cmp_gt_u32 s46, 4
	s_cbranch_scc1 .Lsd11_x
	v_cmp_gt_u32_e32 vcc, 64, v175
	s_cbranch_vccz .Lsd11_x
	s_cmp_eq_u32 s46, 3
	s_cbranch_scc0 .Lsd11_b
	buffer_wbl2 sc1
	s_branch .Lsd11_x

.Lsd11_x:
	v_mul_f32_e32 v157, 0xbfb8aa3b, v124
	v_exp_f32_e32 v157, v157
	v_mul_f32_e32 v160, 0xbfb8aa3b, v125
	v_exp_f32_e32 v160, v160
	v_lshl_or_b32 v148, s54, 7, v152
	v_add_f32_e32 v157, 1.0, v157
	v_rcp_f32_e32 v157, v157
	v_add_f32_e32 v160, 1.0, v160
	v_rcp_f32_e32 v160, v160
	v_lshl_add_u32 v156, s36, 8, v150
	v_mul_f32_e32 v124, v124, v157
	v_mul_f32_e32 v116, v116, v124
	v_mul_f32_e32 v124, v125, v160
	v_mul_f32_e32 v125, 0xbfb8aa3b, v126
	v_exp_f32_e32 v125, v125
	v_mul_f32_e32 v157, 0xbfb8aa3b, v127
	v_exp_f32_e32 v157, v157
	v_mul_f32_e32 v117, v117, v124
	v_add_f32_e32 v124, 1.0, v125
	v_rcp_f32_e32 v124, v124
	v_add_f32_e32 v125, 1.0, v157
	v_rcp_f32_e32 v125, v125
	v_cvt_pk_bf16_f32 v116, v116, v117
	v_mul_f32_e32 v117, v126, v124
	v_mul_f32_e32 v124, 0xbfb8aa3b, v120
	v_exp_f32_e32 v124, v124
	v_mul_f32_e32 v117, v118, v117
	v_mul_f32_e32 v118, v127, v125
	v_mul_f32_e32 v125, 0xbfb8aa3b, v121
	v_exp_f32_e32 v125, v125
	v_mul_f32_e32 v118, v119, v118
	v_add_f32_e32 v119, 1.0, v124
	v_rcp_f32_e32 v119, v119
	v_add_f32_e32 v124, 1.0, v125
	v_rcp_f32_e32 v124, v124
	v_cvt_pk_bf16_f32 v117, v117, v118
	v_mul_f32_e32 v118, v120, v119
	v_mul_f32_e32 v119, 0xbfb8aa3b, v122
	v_exp_f32_e32 v119, v119
	v_mul_f32_e32 v120, 0xbfb8aa3b, v123
	v_exp_f32_e32 v120, v120
	v_mul_f32_e32 v112, v112, v118
	v_mul_f32_e32 v118, v121, v124
	v_mul_f32_e32 v113, v113, v118
	v_add_f32_e32 v118, 1.0, v119
	v_rcp_f32_e32 v119, v118
	v_add_f32_e32 v118, 1.0, v120
	v_rcp_f32_e32 v120, v118
	v_cvt_pk_bf16_f32 v118, v112, v113
	v_mul_f32_e32 v112, v122, v119
	v_mul_f32_e32 v112, v114, v112
	v_mul_f32_e32 v113, v123, v120
	v_mul_f32_e32 v113, v115, v113
	v_cvt_pk_bf16_f32 v119, v112, v113
	v_mul_f32_e32 v113, 0xbfb8aa3b, v108
	v_exp_f32_e32 v114, v113
	v_mul_f32_e32 v113, 0xbfb8aa3b, v109
	v_exp_f32_e32 v115, v113
	v_ashrrev_i32_e32 v149, 31, v148
	v_add_f32_e32 v114, 1.0, v114
	v_rcp_f32_e32 v114, v114
	v_add_f32_e32 v115, 1.0, v115
	v_rcp_f32_e32 v115, v115
	v_mov_b64_e32 v[146:147], s[18:19]
	v_mul_f32_e32 v108, v108, v114
	v_mul_f32_e32 v100, v100, v108
	v_mul_f32_e32 v108, v109, v115
	v_mul_f32_e32 v109, 0xbfb8aa3b, v110
	v_exp_f32_e32 v109, v109
	v_mul_f32_e32 v114, 0xbfb8aa3b, v111
	v_exp_f32_e32 v114, v114
	v_mul_f32_e32 v101, v101, v108
	v_add_f32_e32 v108, 1.0, v109
	v_rcp_f32_e32 v108, v108
	v_mad_i64_i32 v[158:159], s[6:7], v156, s53, v[146:147]
	v_lshlrev_b64 v[148:149], 1, v[148:149]
	v_lshl_add_u64 v[158:159], v[158:159], 0, v[148:149]
	v_add_f32_e32 v109, 1.0, v114
	global_store_dwordx4 v[158:159], v[116:119], off
	v_rcp_f32_e32 v109, v109
	v_cvt_pk_bf16_f32 v100, v100, v101
	v_mul_f32_e32 v101, v110, v108
	v_mul_f32_e32 v108, 0xbfb8aa3b, v104
	v_exp_f32_e32 v108, v108
	v_mul_f32_e32 v101, v102, v101
	v_mul_f32_e32 v102, v111, v109
	v_mul_f32_e32 v109, 0xbfb8aa3b, v105
	v_exp_f32_e32 v109, v109
	v_mul_f32_e32 v102, v103, v102
	v_add_f32_e32 v103, 1.0, v108
	v_rcp_f32_e32 v103, v103
	v_add_f32_e32 v108, 1.0, v109
	v_rcp_f32_e32 v108, v108
	v_cvt_pk_bf16_f32 v101, v101, v102
	v_mul_f32_e32 v102, v104, v103
	v_mul_f32_e32 v103, 0xbfb8aa3b, v106
	v_exp_f32_e32 v103, v103
	v_mul_f32_e32 v104, 0xbfb8aa3b, v107
	v_exp_f32_e32 v104, v104
	v_mul_f32_e32 v96, v96, v102
	v_mul_f32_e32 v102, v105, v108
	v_mul_f32_e32 v97, v97, v102
	v_add_f32_e32 v102, 1.0, v103
	v_rcp_f32_e32 v103, v102
	v_add_f32_e32 v102, 1.0, v104
	v_rcp_f32_e32 v104, v102
	v_cvt_pk_bf16_f32 v102, v96, v97
	v_mul_f32_e32 v96, v106, v103
	v_mul_f32_e32 v96, v98, v96
	v_mul_f32_e32 v97, v107, v104
	v_mul_f32_e32 v97, v99, v97
	v_cvt_pk_bf16_f32 v103, v96, v97
	v_mul_f32_e32 v97, 0xbfb8aa3b, v92
	v_exp_f32_e32 v98, v97
	v_mul_f32_e32 v97, 0xbfb8aa3b, v93
	v_exp_f32_e32 v99, v97
	v_or_b32_e32 v112, 16, v156
	v_add_f32_e32 v98, 1.0, v98
	v_rcp_f32_e32 v98, v98
	v_add_f32_e32 v99, 1.0, v99
	v_rcp_f32_e32 v99, v99
	v_mad_i64_i32 v[112:113], s[6:7], v112, s53, v[146:147]
	v_mul_f32_e32 v92, v92, v98
	v_mul_f32_e32 v84, v84, v92
	v_mul_f32_e32 v92, v93, v99
	v_mul_f32_e32 v93, 0xbfb8aa3b, v94
	v_exp_f32_e32 v93, v93
	v_mul_f32_e32 v98, 0xbfb8aa3b, v95
	v_exp_f32_e32 v98, v98
	v_mul_f32_e32 v85, v85, v92
	v_add_f32_e32 v92, 1.0, v93
	v_rcp_f32_e32 v92, v92
	v_lshl_add_u64 v[112:113], v[112:113], 0, v[148:149]
	v_add_f32_e32 v93, 1.0, v98
	global_store_dwordx4 v[112:113], v[100:103], off
	v_rcp_f32_e32 v93, v93
	v_cvt_pk_bf16_f32 v84, v84, v85
	v_mul_f32_e32 v85, v94, v92
	v_mul_f32_e32 v92, 0xbfb8aa3b, v88
	v_exp_f32_e32 v92, v92
	v_mul_f32_e32 v85, v86, v85
	v_mul_f32_e32 v86, v95, v93
	v_mul_f32_e32 v93, 0xbfb8aa3b, v89
	v_exp_f32_e32 v93, v93
	v_mul_f32_e32 v86, v87, v86
	v_add_f32_e32 v87, 1.0, v92
	v_rcp_f32_e32 v87, v87
	v_add_f32_e32 v92, 1.0, v93
	v_rcp_f32_e32 v92, v92
	v_cvt_pk_bf16_f32 v85, v85, v86
	v_mul_f32_e32 v86, v88, v87
	v_mul_f32_e32 v87, 0xbfb8aa3b, v90
	v_exp_f32_e32 v87, v87
	v_mul_f32_e32 v88, 0xbfb8aa3b, v91
	v_exp_f32_e32 v88, v88
	v_mul_f32_e32 v80, v80, v86
	v_mul_f32_e32 v86, v89, v92
	v_mul_f32_e32 v81, v81, v86
	v_add_f32_e32 v86, 1.0, v87
	v_rcp_f32_e32 v87, v86
	v_add_f32_e32 v86, 1.0, v88
	v_rcp_f32_e32 v88, v86
	v_cvt_pk_bf16_f32 v86, v80, v81
	v_mul_f32_e32 v80, v90, v87
	v_mul_f32_e32 v80, v82, v80
	v_mul_f32_e32 v81, v91, v88
	v_mul_f32_e32 v81, v83, v81
	v_cvt_pk_bf16_f32 v87, v80, v81
	v_mul_f32_e32 v81, 0xbfb8aa3b, v76
	v_exp_f32_e32 v82, v81
	v_mul_f32_e32 v81, 0xbfb8aa3b, v77
	v_exp_f32_e32 v83, v81
	v_or_b32_e32 v96, 32, v156
	v_add_f32_e32 v82, 1.0, v82
	v_rcp_f32_e32 v82, v82
	v_add_f32_e32 v83, 1.0, v83
	v_rcp_f32_e32 v83, v83
	v_mad_i64_i32 v[96:97], s[6:7], v96, s53, v[146:147]
	v_mul_f32_e32 v76, v76, v82
	v_mul_f32_e32 v68, v68, v76
	v_mul_f32_e32 v76, v77, v83
	v_mul_f32_e32 v77, 0xbfb8aa3b, v78
	v_exp_f32_e32 v77, v77
	v_mul_f32_e32 v82, 0xbfb8aa3b, v79
	v_exp_f32_e32 v82, v82
	v_mul_f32_e32 v69, v69, v76
	v_add_f32_e32 v76, 1.0, v77
	v_rcp_f32_e32 v76, v76
	v_lshl_add_u64 v[96:97], v[96:97], 0, v[148:149]
	v_add_f32_e32 v77, 1.0, v82
	global_store_dwordx4 v[96:97], v[84:87], off
	v_rcp_f32_e32 v77, v77
	v_cvt_pk_bf16_f32 v68, v68, v69
	v_mul_f32_e32 v69, v78, v76
	v_mul_f32_e32 v76, 0xbfb8aa3b, v72
	v_exp_f32_e32 v76, v76
	v_mul_f32_e32 v69, v70, v69
	v_mul_f32_e32 v70, v79, v77
	v_mul_f32_e32 v77, 0xbfb8aa3b, v73
	v_exp_f32_e32 v77, v77
	v_mul_f32_e32 v70, v71, v70
	v_add_f32_e32 v71, 1.0, v76
	v_rcp_f32_e32 v71, v71
	v_add_f32_e32 v76, 1.0, v77
	v_rcp_f32_e32 v76, v76
	v_cvt_pk_bf16_f32 v69, v69, v70
	v_mul_f32_e32 v70, v72, v71
	v_mul_f32_e32 v71, 0xbfb8aa3b, v74
	v_exp_f32_e32 v71, v71
	v_mul_f32_e32 v72, 0xbfb8aa3b, v75
	v_exp_f32_e32 v72, v72
	v_mul_f32_e32 v64, v64, v70
	v_mul_f32_e32 v70, v73, v76
	v_mul_f32_e32 v65, v65, v70
	v_add_f32_e32 v70, 1.0, v71
	v_rcp_f32_e32 v71, v70
	v_add_f32_e32 v70, 1.0, v72
	v_rcp_f32_e32 v72, v70
	v_cvt_pk_bf16_f32 v70, v64, v65
	v_mul_f32_e32 v64, v74, v71
	v_mul_f32_e32 v64, v66, v64
	v_mul_f32_e32 v65, v75, v72
	v_mul_f32_e32 v65, v67, v65
	v_cvt_pk_bf16_f32 v71, v64, v65
	v_mul_f32_e32 v65, 0xbfb8aa3b, v60
	v_exp_f32_e32 v66, v65
	v_mul_f32_e32 v65, 0xbfb8aa3b, v61
	v_exp_f32_e32 v67, v65
	v_or_b32_e32 v80, 48, v156
	v_add_f32_e32 v66, 1.0, v66
	v_rcp_f32_e32 v66, v66
	v_add_f32_e32 v67, 1.0, v67
	v_rcp_f32_e32 v67, v67
	v_mad_i64_i32 v[80:81], s[6:7], v80, s53, v[146:147]
	v_mul_f32_e32 v60, v60, v66
	v_mul_f32_e32 v52, v52, v60
	v_mul_f32_e32 v60, v61, v67
	v_mul_f32_e32 v61, 0xbfb8aa3b, v62
	v_exp_f32_e32 v61, v61
	v_mul_f32_e32 v66, 0xbfb8aa3b, v63
	v_exp_f32_e32 v66, v66
	v_mul_f32_e32 v53, v53, v60
	v_add_f32_e32 v60, 1.0, v61
	v_rcp_f32_e32 v60, v60
	v_lshl_add_u64 v[80:81], v[80:81], 0, v[148:149]
	v_add_f32_e32 v61, 1.0, v66
	global_store_dwordx4 v[80:81], v[68:71], off
	v_rcp_f32_e32 v61, v61
	v_cvt_pk_bf16_f32 v52, v52, v53
	v_mul_f32_e32 v53, v62, v60
	v_mul_f32_e32 v60, 0xbfb8aa3b, v56
	v_exp_f32_e32 v60, v60
	v_mul_f32_e32 v53, v54, v53
	v_mul_f32_e32 v54, v63, v61
	v_mul_f32_e32 v61, 0xbfb8aa3b, v57
	v_exp_f32_e32 v61, v61
	v_mul_f32_e32 v54, v55, v54
	v_add_f32_e32 v55, 1.0, v60
	v_rcp_f32_e32 v55, v55
	v_add_f32_e32 v60, 1.0, v61
	v_rcp_f32_e32 v60, v60
	v_cvt_pk_bf16_f32 v53, v53, v54
	v_mul_f32_e32 v54, v56, v55
	v_mul_f32_e32 v55, 0xbfb8aa3b, v58
	v_exp_f32_e32 v55, v55
	v_mul_f32_e32 v56, 0xbfb8aa3b, v59
	v_exp_f32_e32 v56, v56
	v_mul_f32_e32 v48, v48, v54
	v_mul_f32_e32 v54, v57, v60
	v_mul_f32_e32 v49, v49, v54
	v_add_f32_e32 v54, 1.0, v55
	v_rcp_f32_e32 v55, v54
	v_add_f32_e32 v54, 1.0, v56
	v_rcp_f32_e32 v56, v54
	v_cvt_pk_bf16_f32 v54, v48, v49
	v_mul_f32_e32 v48, v58, v55
	v_mul_f32_e32 v48, v50, v48
	v_mul_f32_e32 v49, v59, v56
	v_mul_f32_e32 v49, v51, v49
	v_cvt_pk_bf16_f32 v55, v48, v49
	v_mul_f32_e32 v49, 0xbfb8aa3b, v44
	v_exp_f32_e32 v50, v49
	v_mul_f32_e32 v49, 0xbfb8aa3b, v45
	v_exp_f32_e32 v51, v49
	v_add_u32_e32 v64, 0x80, v156
	v_add_f32_e32 v50, 1.0, v50
	v_rcp_f32_e32 v50, v50
	v_add_f32_e32 v51, 1.0, v51
	v_rcp_f32_e32 v51, v51
	v_mad_i64_i32 v[64:65], s[6:7], v64, s53, v[146:147]
	v_mul_f32_e32 v44, v44, v50
	v_mul_f32_e32 v36, v36, v44
	v_mul_f32_e32 v44, v45, v51
	v_mul_f32_e32 v45, 0xbfb8aa3b, v46
	v_exp_f32_e32 v45, v45
	v_mul_f32_e32 v50, 0xbfb8aa3b, v47
	v_exp_f32_e32 v50, v50
	v_mul_f32_e32 v37, v37, v44
	v_add_f32_e32 v44, 1.0, v45
	v_rcp_f32_e32 v44, v44
	v_lshl_add_u64 v[64:65], v[64:65], 0, v[148:149]
	v_add_f32_e32 v45, 1.0, v50
	global_store_dwordx4 v[64:65], v[52:55], off
	v_rcp_f32_e32 v45, v45
	v_cvt_pk_bf16_f32 v36, v36, v37
	v_mul_f32_e32 v37, v46, v44
	v_mul_f32_e32 v44, 0xbfb8aa3b, v40
	v_exp_f32_e32 v44, v44
	v_mul_f32_e32 v37, v38, v37
	v_mul_f32_e32 v38, v47, v45
	v_mul_f32_e32 v45, 0xbfb8aa3b, v41
	v_exp_f32_e32 v45, v45
	v_mul_f32_e32 v38, v39, v38
	v_add_f32_e32 v39, 1.0, v44
	v_rcp_f32_e32 v39, v39
	v_add_f32_e32 v44, 1.0, v45
	v_rcp_f32_e32 v44, v44
	v_cvt_pk_bf16_f32 v37, v37, v38
	v_mul_f32_e32 v38, v40, v39
	v_mul_f32_e32 v39, 0xbfb8aa3b, v42
	v_exp_f32_e32 v39, v39
	v_mul_f32_e32 v40, 0xbfb8aa3b, v43
	v_exp_f32_e32 v40, v40
	v_mul_f32_e32 v32, v32, v38
	v_mul_f32_e32 v38, v41, v44
	v_mul_f32_e32 v33, v33, v38
	v_add_f32_e32 v38, 1.0, v39
	v_rcp_f32_e32 v39, v38
	v_add_f32_e32 v38, 1.0, v40
	v_rcp_f32_e32 v40, v38
	v_cvt_pk_bf16_f32 v38, v32, v33
	v_mul_f32_e32 v32, v42, v39
	v_mul_f32_e32 v32, v34, v32
	v_mul_f32_e32 v33, v43, v40
	v_mul_f32_e32 v33, v35, v33
	v_cvt_pk_bf16_f32 v39, v32, v33
	v_mul_f32_e32 v33, 0xbfb8aa3b, v28
	v_exp_f32_e32 v34, v33
	v_mul_f32_e32 v33, 0xbfb8aa3b, v29
	v_exp_f32_e32 v35, v33
	v_add_u32_e32 v48, 0x90, v156
	v_add_f32_e32 v34, 1.0, v34
	v_rcp_f32_e32 v34, v34
	v_add_f32_e32 v35, 1.0, v35
	v_rcp_f32_e32 v35, v35
	v_mad_i64_i32 v[48:49], s[6:7], v48, s53, v[146:147]
	v_mul_f32_e32 v28, v28, v34
	v_mul_f32_e32 v20, v20, v28
	v_mul_f32_e32 v28, v29, v35
	v_mul_f32_e32 v29, 0xbfb8aa3b, v30
	v_exp_f32_e32 v29, v29
	v_mul_f32_e32 v34, 0xbfb8aa3b, v31
	v_exp_f32_e32 v34, v34
	v_mul_f32_e32 v21, v21, v28
	v_add_f32_e32 v28, 1.0, v29
	v_rcp_f32_e32 v28, v28
	v_lshl_add_u64 v[48:49], v[48:49], 0, v[148:149]
	v_add_f32_e32 v29, 1.0, v34
	global_store_dwordx4 v[48:49], v[36:39], off
	v_rcp_f32_e32 v29, v29
	v_cvt_pk_bf16_f32 v20, v20, v21
	v_mul_f32_e32 v21, v30, v28
	v_mul_f32_e32 v28, 0xbfb8aa3b, v24
	v_exp_f32_e32 v28, v28
	v_mul_f32_e32 v21, v22, v21
	v_mul_f32_e32 v22, v31, v29
	v_mul_f32_e32 v29, 0xbfb8aa3b, v25
	v_exp_f32_e32 v29, v29
	v_mul_f32_e32 v22, v23, v22
	v_add_f32_e32 v23, 1.0, v28
	v_rcp_f32_e32 v23, v23
	v_add_f32_e32 v28, 1.0, v29
	v_rcp_f32_e32 v28, v28
	v_cvt_pk_bf16_f32 v21, v21, v22
	v_mul_f32_e32 v22, v24, v23
	v_mul_f32_e32 v23, 0xbfb8aa3b, v26
	v_exp_f32_e32 v23, v23
	v_mul_f32_e32 v24, 0xbfb8aa3b, v27
	v_exp_f32_e32 v24, v24
	v_mul_f32_e32 v16, v16, v22
	v_mul_f32_e32 v22, v25, v28
	v_mul_f32_e32 v17, v17, v22
	v_add_f32_e32 v22, 1.0, v23
	v_rcp_f32_e32 v23, v22
	v_add_f32_e32 v22, 1.0, v24
	v_rcp_f32_e32 v24, v22
	v_cvt_pk_bf16_f32 v22, v16, v17
	v_mul_f32_e32 v16, v26, v23
	v_mul_f32_e32 v16, v18, v16
	v_mul_f32_e32 v17, v27, v24
	v_mul_f32_e32 v17, v19, v17
	v_cvt_pk_bf16_f32 v23, v16, v17
	v_mul_f32_e32 v17, 0xbfb8aa3b, v12
	v_exp_f32_e32 v18, v17
	v_mul_f32_e32 v17, 0xbfb8aa3b, v13
	v_exp_f32_e32 v19, v17
	v_add_u32_e32 v32, 0xa0, v156
	v_add_f32_e32 v18, 1.0, v18
	v_rcp_f32_e32 v18, v18
	v_add_f32_e32 v19, 1.0, v19
	v_rcp_f32_e32 v19, v19
	v_mad_i64_i32 v[32:33], s[6:7], v32, s53, v[146:147]
	v_mul_f32_e32 v12, v12, v18
	v_mul_f32_e32 v4, v4, v12
	v_mul_f32_e32 v12, v13, v19
	v_mul_f32_e32 v13, 0xbfb8aa3b, v14
	v_exp_f32_e32 v13, v13
	v_mul_f32_e32 v18, 0xbfb8aa3b, v15
	v_exp_f32_e32 v18, v18
	v_mul_f32_e32 v5, v5, v12
	v_add_f32_e32 v12, 1.0, v13
	v_rcp_f32_e32 v12, v12
	v_lshl_add_u64 v[32:33], v[32:33], 0, v[148:149]
	v_add_f32_e32 v13, 1.0, v18
	global_store_dwordx4 v[32:33], v[20:23], off
	v_rcp_f32_e32 v13, v13
	v_cvt_pk_bf16_f32 v4, v4, v5
	v_mul_f32_e32 v5, v14, v12
	v_mul_f32_e32 v12, 0xbfb8aa3b, v8
	v_exp_f32_e32 v12, v12
	v_mul_f32_e32 v5, v6, v5
	v_mul_f32_e32 v6, v15, v13
	v_mul_f32_e32 v13, 0xbfb8aa3b, v9
	v_exp_f32_e32 v13, v13
	v_mul_f32_e32 v6, v7, v6
	v_add_f32_e32 v7, 1.0, v12
	v_rcp_f32_e32 v7, v7
	v_add_f32_e32 v12, 1.0, v13
	v_rcp_f32_e32 v12, v12
	v_cvt_pk_bf16_f32 v5, v5, v6
	v_mul_f32_e32 v6, v8, v7
	v_mul_f32_e32 v7, 0xbfb8aa3b, v10
	v_exp_f32_e32 v7, v7
	v_mul_f32_e32 v8, 0xbfb8aa3b, v11
	v_exp_f32_e32 v8, v8
	v_mul_f32_e32 v0, v0, v6
	v_mul_f32_e32 v6, v9, v12
	v_mul_f32_e32 v1, v1, v6
	v_add_f32_e32 v6, 1.0, v7
	v_rcp_f32_e32 v7, v6
	v_add_f32_e32 v6, 1.0, v8
	v_rcp_f32_e32 v8, v6
	v_add_u32_e32 v16, 0xb0, v156
	v_mad_i64_i32 v[16:17], s[6:7], v16, s53, v[146:147]
	v_lshl_add_u64 v[16:17], v[16:17], 0, v[148:149]
	v_cvt_pk_bf16_f32 v6, v0, v1
	v_mul_f32_e32 v0, v10, v7
	v_mul_f32_e32 v1, v11, v8
	s_andn2_b64 vcc, exec, s[0:1]
	s_mov_b64 s[0:1], -1
	v_mul_f32_e32 v0, v2, v0
	v_mul_f32_e32 v1, v3, v1
	v_cvt_pk_bf16_f32 v7, v0, v1
	global_store_dwordx4 v[16:17], v[4:7], off
	s_cmp_lt_i32 s36, 64
	s_cbranch_scc1 .Lsd11_e
	s_add_u32 s99, s99, 1

.LBB0_1230:
	s_cmp_gt_i32 s85, 12
	s_cselect_b64 s[0:1], -1, 0
	s_and_b64 s[4:5], s[4:5], s[0:1]
	s_andn2_b64 vcc, exec, s[4:5]
	s_cbranch_vccnz .LBB0_1282
	s_cmp_gt_u32 s98, 2
	s_cbranch_scc1 .Ltg11_no
	s_bitcmp1_b32 s98, 0
	s_cbranch_scc1 .Ltg11_no
	s_cmp_lt_u32 s2, 172
	s_cbranch_scc1 .Ltg11_no
	s_cmp_gt_u32 s2, 251
	s_cbranch_scc1 .Ltg11_no
	s_mov_b32 s98, 3
	s_branch .Ld12_body

.Ld12_body:
	s_cmpk_lg_i32 s34, 0x100
	s_cselect_b64 s[4:5], -1, 0
	s_cmpk_gt_i32 s2, 0x57
	s_cselect_b64 s[6:7], -1, 0
	s_mov_b64 s[8:9], -1
	v_readfirstlane_b32 s16, v175
	s_and_b64 vcc, exec, s[8:9]
	s_cbranch_vccz .LBB0_1286
	s_cmpk_gt_i32 s2, 0xff
	s_mov_b64 s[10:11], 0
	s_cbranch_scc0 .LBB0_1287
	s_add_u32 s4, s2, 0xffffff00
	s_addc_u32 s5, 0, -1
	s_waitcnt vmcnt(0)
	v_mov_b64_e32 v[0:1], 0x58
	v_cmp_lt_u64_e64 s[6:7], s[4:5], v[0:1]
	s_mov_b64 s[12:13], 0
	s_andn2_b64 vcc, exec, s[12:13]
	s_cbranch_vccnz .LBB0_1293
	s_branch .LBB0_1288

.LBB0_1334:
	s_cmp_lg_u32 s98, 3
	s_cbranch_scc1 .Ld12_cont
	s_mov_b32 s98, 4
	s_cmp_gt_i32 s85, 12
	s_cselect_b64 s[0:1], -1, 0
	v_readlane_b32 s99, v255, 63
	v_mbcnt_lo_u32_b32 v175, -1, 0
	v_mbcnt_hi_u32_b32 v175, -1, v175
	s_nop 1
	v_add_u32_e32 v175, s99, v175
	s_branch .Ltg11_no
